# skinny (meta-row) GEMMs: operand load pairs issued back to back instead of one drained pair at a time
# speedup vs baseline: 1.0397x; 1.0040x over previous
; template <class SE> __device__ __forceinline__ void skinny_gemm(const Frame& F, const bf16* Am, const bf16* Bt, int ntiles, int K, const SE& E) {
;     ...
;         for (int s0 = sb; s0 < se; s0 += 8) {
;             const int n = (se - s0) < 8 ? (se - s0) : 8;
;             bf16x8 av[8], bv[8], cv[8];
; #pragma unroll
;             for (int q = 0; q < 8; ++q) if (q < n) { av[q] = *(const bf16x8*)(ap + 32 * (s0 + q)); bv[q] = *(const bf16x8*)(b0 + 32 * (s0 + q)); if (SE::DUAL) cv[q] = *(const bf16x8*)(b1 + 32 * (s0 + q)); }
.LBB0_185:
	s_cmp_gt_i32 s19, 0
	s_cselect_b64 s[28:29], -1, 0
	s_cmp_lt_i32 s19, 1
	s_cbranch_scc1 .LBB0_187
	s_ashr_i32 s27, s26, 31
	s_lshl_b64 s[30:31], s[26:27], 1
	v_lshl_add_u64 v[32:33], v[74:75], 0, s[30:31]
	v_lshl_add_u64 v[0:1], v[68:69], 0, s[30:31]
	global_load_dwordx4 v[0:3], v[0:1], off
	s_nop 0
	global_load_dwordx4 v[32:35], v[32:33], off

; template <class SE> __device__ __forceinline__ void skinny_gemm(const Frame& F, const bf16* Am, const bf16* Bt, int ntiles, int K, const SE& E) {
;     ...
;         for (int s0 = sb; s0 < se; s0 += 8) {
;             const int n = (se - s0) < 8 ? (se - s0) : 8;
;             bf16x8 av[8], bv[8], cv[8];
; #pragma unroll
;             for (int q = 0; q < 8; ++q) if (q < n) { av[q] = *(const bf16x8*)(ap + 32 * (s0 + q)); bv[q] = *(const bf16x8*)(b0 + 32 * (s0 + q)); if (SE::DUAL) cv[q] = *(const bf16x8*)(b1 + 32 * (s0 + q)); }
.LBB0_203:
	s_ashr_i32 s27, s26, 31
	s_lshl_b64 s[34:35], s[26:27], 1
	v_lshl_add_u64 v[28:29], v[74:75], 0, s[34:35]
	v_lshl_add_u64 v[30:31], v[68:69], 0, s[34:35]
	global_load_dwordx4 v[36:39], v[30:31], off offset:64
	s_nop 0
	global_load_dwordx4 v[28:31], v[28:29], off offset:64
	s_cmp_gt_i32 s19, 2
	s_cselect_b64 s[34:35], -1, 0
	s_cmp_lt_i32 s19, 3
	s_cbranch_scc1 .LBB0_189
.LBB0_204:
	s_ashr_i32 s27, s26, 31
	s_lshl_b64 s[36:37], s[26:27], 1
	v_lshl_add_u64 v[24:25], v[74:75], 0, s[36:37]
	v_lshl_add_u64 v[26:27], v[68:69], 0, s[36:37]
	global_load_dwordx4 v[40:43], v[26:27], off offset:128
	s_nop 0
	global_load_dwordx4 v[24:27], v[24:25], off offset:128
	s_cmp_gt_i32 s19, 3
	s_cselect_b64 s[36:37], -1, 0
	s_cmp_lt_i32 s19, 4
	s_cbranch_scc1 .LBB0_190
.LBB0_205:
	s_ashr_i32 s27, s26, 31
	s_lshl_b64 s[38:39], s[26:27], 1
	v_lshl_add_u64 v[20:21], v[74:75], 0, s[38:39]
	v_lshl_add_u64 v[22:23], v[68:69], 0, s[38:39]
	global_load_dwordx4 v[44:47], v[22:23], off offset:192
	s_nop 0
	global_load_dwordx4 v[20:23], v[20:21], off offset:192
	s_cmp_gt_i32 s19, 4
	s_cselect_b64 s[38:39], -1, 0
	s_cmp_lt_i32 s19, 5
	s_cbranch_scc1 .LBB0_191
.LBB0_206:
	s_ashr_i32 s27, s26, 31
	s_lshl_b64 s[40:41], s[26:27], 1
	v_lshl_add_u64 v[16:17], v[74:75], 0, s[40:41]
	v_lshl_add_u64 v[18:19], v[68:69], 0, s[40:41]
	global_load_dwordx4 v[48:51], v[18:19], off offset:256
	s_nop 0
	global_load_dwordx4 v[16:19], v[16:17], off offset:256
	s_cmp_gt_i32 s19, 5
	s_cselect_b64 s[40:41], -1, 0
	s_cmp_lt_i32 s19, 6
	s_cbranch_scc1 .LBB0_192
.LBB0_207:
	s_ashr_i32 s27, s26, 31
	s_lshl_b64 s[42:43], s[26:27], 1
	v_lshl_add_u64 v[12:13], v[74:75], 0, s[42:43]
	v_lshl_add_u64 v[14:15], v[68:69], 0, s[42:43]
	global_load_dwordx4 v[52:55], v[14:15], off offset:320
	s_nop 0
	global_load_dwordx4 v[12:15], v[12:13], off offset:320
	s_cmp_gt_i32 s19, 6
	s_cselect_b64 s[42:43], -1, 0
	s_cmp_lt_i32 s19, 7
	s_cbranch_scc1 .LBB0_193
.LBB0_208:
	s_ashr_i32 s27, s26, 31
	s_lshl_b64 s[44:45], s[26:27], 1
	v_lshl_add_u64 v[8:9], v[74:75], 0, s[44:45]
	v_lshl_add_u64 v[10:11], v[68:69], 0, s[44:45]
	global_load_dwordx4 v[56:59], v[10:11], off offset:384
	s_nop 0
	global_load_dwordx4 v[8:11], v[8:9], off offset:384
	s_cmp_gt_i32 s19, 7
	s_cselect_b64 s[44:45], -1, 0
	s_cmp_lt_i32 s19, 8
	s_cbranch_scc1 .LBB0_194
.LBB0_209:
	s_ashr_i32 s27, s26, 31
	s_lshl_b64 s[46:47], s[26:27], 1
	v_lshl_add_u64 v[4:5], v[74:75], 0, s[46:47]
	v_lshl_add_u64 v[6:7], v[68:69], 0, s[46:47]
	global_load_dwordx4 v[60:63], v[6:7], off offset:448
	s_nop 0
	global_load_dwordx4 v[4:7], v[4:5], off offset:448
	s_andn2_b64 vcc, exec, s[28:29]
	s_cbranch_vccz .LBB0_195
	s_branch .LBB0_196

; template <class SE> __device__ __forceinline__ void skinny_gemm(const Frame& F, const bf16* Am, const bf16* Bt, int ntiles, int K, const SE& E) {
;     ...
;         for (int s0 = sb; s0 < se; s0 += 8) {
;             const int n = (se - s0) < 8 ? (se - s0) : 8;
;             bf16x8 av[8], bv[8], cv[8];
; #pragma unroll
;             for (int q = 0; q < 8; ++q) if (q < n) { av[q] = *(const bf16x8*)(ap + 32 * (s0 + q)); bv[q] = *(const bf16x8*)(b0 + 32 * (s0 + q)); if (SE::DUAL) cv[q] = *(const bf16x8*)(b1 + 32 * (s0 + q)); }
.LBB0_580:
	s_cmp_gt_i32 s15, 0
	s_cselect_b64 s[18:19], -1, 0
	s_cmp_lt_i32 s15, 1
	s_cbranch_scc1 .LBB0_582
	s_ashr_i32 s17, s16, 31
	s_lshl_b64 s[20:21], s[16:17], 1
	v_lshl_add_u64 v[32:33], v[74:75], 0, s[20:21]
	v_lshl_add_u64 v[0:1], v[68:69], 0, s[20:21]
	global_load_dwordx4 v[0:3], v[0:1], off
	s_nop 0
	global_load_dwordx4 v[32:35], v[32:33], off

; template <class SE> __device__ __forceinline__ void skinny_gemm(const Frame& F, const bf16* Am, const bf16* Bt, int ntiles, int K, const SE& E) {
;     ...
;         for (int s0 = sb; s0 < se; s0 += 8) {
;             const int n = (se - s0) < 8 ? (se - s0) : 8;
;             bf16x8 av[8], bv[8], cv[8];
; #pragma unroll
;             for (int q = 0; q < 8; ++q) if (q < n) { av[q] = *(const bf16x8*)(ap + 32 * (s0 + q)); bv[q] = *(const bf16x8*)(b0 + 32 * (s0 + q)); if (SE::DUAL) cv[q] = *(const bf16x8*)(b1 + 32 * (s0 + q)); }
.LBB0_598:
	s_ashr_i32 s17, s16, 31
	s_lshl_b64 s[22:23], s[16:17], 1
	v_lshl_add_u64 v[28:29], v[74:75], 0, s[22:23]
	v_lshl_add_u64 v[30:31], v[68:69], 0, s[22:23]
	global_load_dwordx4 v[36:39], v[30:31], off offset:64
	s_nop 0
	global_load_dwordx4 v[28:31], v[28:29], off offset:64
	s_cmp_gt_i32 s15, 2
	s_cselect_b64 s[22:23], -1, 0
	s_cmp_lt_i32 s15, 3
	s_cbranch_scc1 .LBB0_584
.LBB0_599:
	s_ashr_i32 s17, s16, 31
	s_lshl_b64 s[24:25], s[16:17], 1
	v_lshl_add_u64 v[24:25], v[74:75], 0, s[24:25]
	v_lshl_add_u64 v[26:27], v[68:69], 0, s[24:25]
	global_load_dwordx4 v[40:43], v[26:27], off offset:128
	s_nop 0
	global_load_dwordx4 v[24:27], v[24:25], off offset:128
	s_cmp_gt_i32 s15, 3
	s_cselect_b64 s[24:25], -1, 0
	s_cmp_lt_i32 s15, 4
	s_cbranch_scc1 .LBB0_585
.LBB0_600:
	s_ashr_i32 s17, s16, 31
	s_lshl_b64 s[26:27], s[16:17], 1
	v_lshl_add_u64 v[20:21], v[74:75], 0, s[26:27]
	v_lshl_add_u64 v[22:23], v[68:69], 0, s[26:27]
	global_load_dwordx4 v[44:47], v[22:23], off offset:192
	s_nop 0
	global_load_dwordx4 v[20:23], v[20:21], off offset:192
	s_cmp_gt_i32 s15, 4
	s_cselect_b64 s[26:27], -1, 0
	s_cmp_lt_i32 s15, 5
	s_cbranch_scc1 .LBB0_586
.LBB0_601:
	s_ashr_i32 s17, s16, 31
	s_lshl_b64 s[28:29], s[16:17], 1
	v_lshl_add_u64 v[16:17], v[74:75], 0, s[28:29]
	v_lshl_add_u64 v[18:19], v[68:69], 0, s[28:29]
	global_load_dwordx4 v[48:51], v[18:19], off offset:256
	s_nop 0
	global_load_dwordx4 v[16:19], v[16:17], off offset:256
	s_cmp_gt_i32 s15, 5
	s_cselect_b64 s[28:29], -1, 0
	s_cmp_lt_i32 s15, 6
	s_cbranch_scc1 .LBB0_587
.LBB0_602:
	s_ashr_i32 s17, s16, 31
	s_lshl_b64 s[30:31], s[16:17], 1
	v_lshl_add_u64 v[12:13], v[74:75], 0, s[30:31]
	v_lshl_add_u64 v[14:15], v[68:69], 0, s[30:31]
	global_load_dwordx4 v[52:55], v[14:15], off offset:320
	s_nop 0
	global_load_dwordx4 v[12:15], v[12:13], off offset:320
	s_cmp_gt_i32 s15, 6
	s_cselect_b64 s[30:31], -1, 0
	s_cmp_lt_i32 s15, 7
	s_cbranch_scc1 .LBB0_588
.LBB0_603:
	s_ashr_i32 s17, s16, 31
	s_lshl_b64 s[34:35], s[16:17], 1
	v_lshl_add_u64 v[8:9], v[74:75], 0, s[34:35]
	v_lshl_add_u64 v[10:11], v[68:69], 0, s[34:35]
	global_load_dwordx4 v[56:59], v[10:11], off offset:384
	s_nop 0
	global_load_dwordx4 v[8:11], v[8:9], off offset:384
	s_cmp_gt_i32 s15, 7
	s_cselect_b64 s[34:35], -1, 0
	s_cmp_lt_i32 s15, 8
	s_cbranch_scc1 .LBB0_589
.LBB0_604:
	s_ashr_i32 s17, s16, 31
	s_lshl_b64 s[46:47], s[16:17], 1
	v_lshl_add_u64 v[4:5], v[74:75], 0, s[46:47]
	v_lshl_add_u64 v[6:7], v[68:69], 0, s[46:47]
	global_load_dwordx4 v[60:63], v[6:7], off offset:448
	s_nop 0
	global_load_dwordx4 v[4:7], v[4:5], off offset:448
	s_andn2_b64 vcc, exec, s[18:19]
	s_cbranch_vccz .LBB0_590
	s_branch .LBB0_591

; template <class SE> __device__ __forceinline__ void skinny_gemm(const Frame& F, const bf16* Am, const bf16* Bt, int ntiles, int K, const SE& E) {
;     ...
;         for (int s0 = sb; s0 < se; s0 += 8) {
;             const int n = (se - s0) < 8 ? (se - s0) : 8;
;             bf16x8 av[8], bv[8], cv[8];
; #pragma unroll
;             for (int q = 0; q < 8; ++q) if (q < n) { av[q] = *(const bf16x8*)(ap + 32 * (s0 + q)); bv[q] = *(const bf16x8*)(b0 + 32 * (s0 + q)); if (SE::DUAL) cv[q] = *(const bf16x8*)(b1 + 32 * (s0 + q)); }
.LBB0_645:
	s_cmp_gt_i32 s7, 0
	s_cselect_b64 s[14:15], -1, 0
	s_cmp_lt_i32 s7, 1
	s_cbranch_scc1 .LBB0_647
	s_ashr_i32 s13, s12, 31
	s_lshl_b64 s[16:17], s[12:13], 1
	v_lshl_add_u64 v[32:33], v[74:75], 0, s[16:17]
	v_lshl_add_u64 v[0:1], v[68:69], 0, s[16:17]
	global_load_dwordx4 v[0:3], v[0:1], off
	s_nop 0
	global_load_dwordx4 v[32:35], v[32:33], off

; template <class SE> __device__ __forceinline__ void skinny_gemm(const Frame& F, const bf16* Am, const bf16* Bt, int ntiles, int K, const SE& E) {
;     ...
;         for (int s0 = sb; s0 < se; s0 += 8) {
;             const int n = (se - s0) < 8 ? (se - s0) : 8;
;             bf16x8 av[8], bv[8], cv[8];
; #pragma unroll
;             for (int q = 0; q < 8; ++q) if (q < n) { av[q] = *(const bf16x8*)(ap + 32 * (s0 + q)); bv[q] = *(const bf16x8*)(b0 + 32 * (s0 + q)); if (SE::DUAL) cv[q] = *(const bf16x8*)(b1 + 32 * (s0 + q)); }
.LBB0_663:
	s_ashr_i32 s13, s12, 31
	s_lshl_b64 s[18:19], s[12:13], 1
	v_lshl_add_u64 v[28:29], v[74:75], 0, s[18:19]
	v_lshl_add_u64 v[30:31], v[68:69], 0, s[18:19]
	global_load_dwordx4 v[36:39], v[30:31], off offset:64
	s_nop 0
	global_load_dwordx4 v[28:31], v[28:29], off offset:64
	s_cmp_gt_i32 s7, 2
	s_cselect_b64 s[18:19], -1, 0
	s_cmp_lt_i32 s7, 3
	s_cbranch_scc1 .LBB0_649
.LBB0_664:
	s_ashr_i32 s13, s12, 31
	s_lshl_b64 s[20:21], s[12:13], 1
	v_lshl_add_u64 v[24:25], v[74:75], 0, s[20:21]
	v_lshl_add_u64 v[26:27], v[68:69], 0, s[20:21]
	global_load_dwordx4 v[40:43], v[26:27], off offset:128
	s_nop 0
	global_load_dwordx4 v[24:27], v[24:25], off offset:128
	s_cmp_gt_i32 s7, 3
	s_cselect_b64 s[20:21], -1, 0
	s_cmp_lt_i32 s7, 4
	s_cbranch_scc1 .LBB0_650
.LBB0_665:
	s_ashr_i32 s13, s12, 31
	s_lshl_b64 s[22:23], s[12:13], 1
	v_lshl_add_u64 v[20:21], v[74:75], 0, s[22:23]
	v_lshl_add_u64 v[22:23], v[68:69], 0, s[22:23]
	global_load_dwordx4 v[44:47], v[22:23], off offset:192
	s_nop 0
	global_load_dwordx4 v[20:23], v[20:21], off offset:192
	s_cmp_gt_i32 s7, 4
	s_cselect_b64 s[22:23], -1, 0
	s_cmp_lt_i32 s7, 5
	s_cbranch_scc1 .LBB0_651
.LBB0_666:
	s_ashr_i32 s13, s12, 31
	s_lshl_b64 s[24:25], s[12:13], 1
	v_lshl_add_u64 v[16:17], v[74:75], 0, s[24:25]
	v_lshl_add_u64 v[18:19], v[68:69], 0, s[24:25]
	global_load_dwordx4 v[48:51], v[18:19], off offset:256
	s_nop 0
	global_load_dwordx4 v[16:19], v[16:17], off offset:256
	s_cmp_gt_i32 s7, 5
	s_cselect_b64 s[24:25], -1, 0
	s_cmp_lt_i32 s7, 6
	s_cbranch_scc1 .LBB0_652
.LBB0_667:
	s_ashr_i32 s13, s12, 31
	s_lshl_b64 s[26:27], s[12:13], 1
	v_lshl_add_u64 v[12:13], v[74:75], 0, s[26:27]
	v_lshl_add_u64 v[14:15], v[68:69], 0, s[26:27]
	global_load_dwordx4 v[52:55], v[14:15], off offset:320
	s_nop 0
	global_load_dwordx4 v[12:15], v[12:13], off offset:320
	s_cmp_gt_i32 s7, 6
	s_cselect_b64 s[26:27], -1, 0
	s_cmp_lt_i32 s7, 7
	s_cbranch_scc1 .LBB0_653
.LBB0_668:
	s_ashr_i32 s13, s12, 31
	s_lshl_b64 s[28:29], s[12:13], 1
	v_lshl_add_u64 v[8:9], v[74:75], 0, s[28:29]
	v_lshl_add_u64 v[10:11], v[68:69], 0, s[28:29]
	global_load_dwordx4 v[56:59], v[10:11], off offset:384
	s_nop 0
	global_load_dwordx4 v[8:11], v[8:9], off offset:384
	s_cmp_gt_i32 s7, 7
	s_cselect_b64 s[28:29], -1, 0
	s_cmp_lt_i32 s7, 8
	s_cbranch_scc1 .LBB0_654
.LBB0_669:
	s_ashr_i32 s13, s12, 31
	s_lshl_b64 s[40:41], s[12:13], 1
	v_lshl_add_u64 v[4:5], v[74:75], 0, s[40:41]
	v_lshl_add_u64 v[6:7], v[68:69], 0, s[40:41]
	global_load_dwordx4 v[60:63], v[6:7], off offset:448
	s_nop 0
	global_load_dwordx4 v[4:7], v[4:5], off offset:448
	s_andn2_b64 vcc, exec, s[14:15]
	s_cbranch_vccz .LBB0_655
	s_branch .LBB0_656

; template <class SE> __device__ __forceinline__ void skinny_gemm(const Frame& F, const bf16* Am, const bf16* Bt, int ntiles, int K, const SE& E) {
;     ...
;         for (int s0 = sb; s0 < se; s0 += 8) {
;             const int n = (se - s0) < 8 ? (se - s0) : 8;
;             bf16x8 av[8], bv[8], cv[8];
; #pragma unroll
;             for (int q = 0; q < 8; ++q) if (q < n) { av[q] = *(const bf16x8*)(ap + 32 * (s0 + q)); bv[q] = *(const bf16x8*)(b0 + 32 * (s0 + q)); if (SE::DUAL) cv[q] = *(const bf16x8*)(b1 + 32 * (s0 + q)); }
.LBB0_762:
	s_cmp_gt_i32 s5, 0
	s_cselect_b64 s[8:9], -1, 0
	s_cmp_lt_i32 s5, 1
	s_cbranch_scc1 .LBB0_764
	s_ashr_i32 s7, s6, 31
	s_lshl_b64 s[10:11], s[6:7], 1
	v_lshl_add_u64 v[32:33], v[74:75], 0, s[10:11]
	v_lshl_add_u64 v[0:1], v[68:69], 0, s[10:11]
	global_load_dwordx4 v[0:3], v[0:1], off
	s_nop 0
	global_load_dwordx4 v[32:35], v[32:33], off

; template <class SE> __device__ __forceinline__ void skinny_gemm(const Frame& F, const bf16* Am, const bf16* Bt, int ntiles, int K, const SE& E) {
;     ...
;         for (int s0 = sb; s0 < se; s0 += 8) {
;             const int n = (se - s0) < 8 ? (se - s0) : 8;
;             bf16x8 av[8], bv[8], cv[8];
; #pragma unroll
;             for (int q = 0; q < 8; ++q) if (q < n) { av[q] = *(const bf16x8*)(ap + 32 * (s0 + q)); bv[q] = *(const bf16x8*)(b0 + 32 * (s0 + q)); if (SE::DUAL) cv[q] = *(const bf16x8*)(b1 + 32 * (s0 + q)); }
.LBB0_780:
	s_ashr_i32 s7, s6, 31
	s_lshl_b64 s[12:13], s[6:7], 1
	v_lshl_add_u64 v[28:29], v[74:75], 0, s[12:13]
	v_lshl_add_u64 v[30:31], v[68:69], 0, s[12:13]
	global_load_dwordx4 v[36:39], v[30:31], off offset:64
	s_nop 0
	global_load_dwordx4 v[28:31], v[28:29], off offset:64
	s_cmp_gt_i32 s5, 2
	s_cselect_b64 s[12:13], -1, 0
	s_cmp_lt_i32 s5, 3
	s_cbranch_scc1 .LBB0_766
.LBB0_781:
	s_ashr_i32 s7, s6, 31
	s_lshl_b64 s[14:15], s[6:7], 1
	v_lshl_add_u64 v[24:25], v[74:75], 0, s[14:15]
	v_lshl_add_u64 v[26:27], v[68:69], 0, s[14:15]
	global_load_dwordx4 v[40:43], v[26:27], off offset:128
	s_nop 0
	global_load_dwordx4 v[24:27], v[24:25], off offset:128
	s_cmp_gt_i32 s5, 3
	s_cselect_b64 s[14:15], -1, 0
	s_cmp_lt_i32 s5, 4
	s_cbranch_scc1 .LBB0_767
.LBB0_782:
	s_ashr_i32 s7, s6, 31
	s_lshl_b64 s[16:17], s[6:7], 1
	v_lshl_add_u64 v[20:21], v[74:75], 0, s[16:17]
	v_lshl_add_u64 v[22:23], v[68:69], 0, s[16:17]
	global_load_dwordx4 v[44:47], v[22:23], off offset:192
	s_nop 0
	global_load_dwordx4 v[20:23], v[20:21], off offset:192
	s_cmp_gt_i32 s5, 4
	s_cselect_b64 s[16:17], -1, 0
	s_cmp_lt_i32 s5, 5
	s_cbranch_scc1 .LBB0_768
.LBB0_783:
	s_ashr_i32 s7, s6, 31
	s_lshl_b64 s[18:19], s[6:7], 1
	v_lshl_add_u64 v[16:17], v[74:75], 0, s[18:19]
	v_lshl_add_u64 v[18:19], v[68:69], 0, s[18:19]
	global_load_dwordx4 v[48:51], v[18:19], off offset:256
	s_nop 0
	global_load_dwordx4 v[16:19], v[16:17], off offset:256
	s_cmp_gt_i32 s5, 5
	s_cselect_b64 s[18:19], -1, 0
	s_cmp_lt_i32 s5, 6
	s_cbranch_scc1 .LBB0_769
.LBB0_784:
	s_ashr_i32 s7, s6, 31
	s_lshl_b64 s[20:21], s[6:7], 1
	v_lshl_add_u64 v[12:13], v[74:75], 0, s[20:21]
	v_lshl_add_u64 v[14:15], v[68:69], 0, s[20:21]
	global_load_dwordx4 v[52:55], v[14:15], off offset:320
	s_nop 0
	global_load_dwordx4 v[12:15], v[12:13], off offset:320
	s_cmp_gt_i32 s5, 6
	s_cselect_b64 s[20:21], -1, 0
	s_cmp_lt_i32 s5, 7
	s_cbranch_scc1 .LBB0_770
.LBB0_785:
	s_ashr_i32 s7, s6, 31
	s_lshl_b64 s[22:23], s[6:7], 1
	v_lshl_add_u64 v[8:9], v[74:75], 0, s[22:23]
	v_lshl_add_u64 v[10:11], v[68:69], 0, s[22:23]
	global_load_dwordx4 v[56:59], v[10:11], off offset:384
	s_nop 0
	global_load_dwordx4 v[8:11], v[8:9], off offset:384
	s_cmp_gt_i32 s5, 7
	s_cselect_b64 s[22:23], -1, 0
	s_cmp_lt_i32 s5, 8
	s_cbranch_scc1 .LBB0_771
.LBB0_786:
	s_ashr_i32 s7, s6, 31
	s_lshl_b64 s[30:31], s[6:7], 1
	v_lshl_add_u64 v[4:5], v[74:75], 0, s[30:31]
	v_lshl_add_u64 v[6:7], v[68:69], 0, s[30:31]
	global_load_dwordx4 v[60:63], v[6:7], off offset:448
	s_nop 0
	global_load_dwordx4 v[4:7], v[4:5], off offset:448
	s_andn2_b64 vcc, exec, s[8:9]
	s_cbranch_vccz .LBB0_772
	s_branch .LBB0_773

; template <class SE> __device__ __forceinline__ void skinny_gemm(const Frame& F, const bf16* Am, const bf16* Bt, int ntiles, int K, const SE& E) {
;     ...
;         for (int s0 = sb; s0 < se; s0 += 8) {
;             const int n = (se - s0) < 8 ? (se - s0) : 8;
;             bf16x8 av[8], bv[8], cv[8];
; #pragma unroll
;             for (int q = 0; q < 8; ++q) if (q < n) { av[q] = *(const bf16x8*)(ap + 32 * (s0 + q)); bv[q] = *(const bf16x8*)(b0 + 32 * (s0 + q)); if (SE::DUAL) cv[q] = *(const bf16x8*)(b1 + 32 * (s0 + q)); }
.LBB0_992:
	s_cmp_gt_i32 s3, 0
	s_cselect_b64 s[10:11], -1, 0
	s_cmp_lt_i32 s3, 1
	s_cbranch_scc1 .LBB0_994
	s_ashr_i32 s9, s8, 31
	s_lshl_b64 s[12:13], s[8:9], 1
	v_lshl_add_u64 v[0:1], v[108:109], 0, s[12:13]
	v_lshl_add_u64 v[32:33], v[114:115], 0, s[12:13]
	v_lshl_add_u64 v[64:65], v[116:117], 0, s[12:13]
	global_load_dwordx4 v[0:3], v[0:1], off
	s_nop 0
	global_load_dwordx4 v[32:35], v[32:33], off
	s_nop 0
	global_load_dwordx4 v[64:67], v[64:65], off

; template <class SE> __device__ __forceinline__ void skinny_gemm(const Frame& F, const bf16* Am, const bf16* Bt, int ntiles, int K, const SE& E) {
;     ...
;         for (int s0 = sb; s0 < se; s0 += 8) {
;             const int n = (se - s0) < 8 ? (se - s0) : 8;
;             bf16x8 av[8], bv[8], cv[8];
; #pragma unroll
;             for (int q = 0; q < 8; ++q) if (q < n) { av[q] = *(const bf16x8*)(ap + 32 * (s0 + q)); bv[q] = *(const bf16x8*)(b0 + 32 * (s0 + q)); if (SE::DUAL) cv[q] = *(const bf16x8*)(b1 + 32 * (s0 + q)); }
.LBB0_1010:
	s_ashr_i32 s9, s8, 31
	s_lshl_b64 s[14:15], s[8:9], 1
	v_lshl_add_u64 v[28:29], v[108:109], 0, s[14:15]
	v_lshl_add_u64 v[30:31], v[114:115], 0, s[14:15]
	v_lshl_add_u64 v[60:61], v[116:117], 0, s[14:15]
	global_load_dwordx4 v[68:71], v[28:29], off offset:64
	s_nop 0
	global_load_dwordx4 v[28:31], v[30:31], off offset:64
	s_nop 0
	global_load_dwordx4 v[60:63], v[60:61], off offset:64
	s_cmp_gt_i32 s3, 2
	s_cselect_b64 s[14:15], -1, 0
	s_cmp_lt_i32 s3, 3
	s_cbranch_scc1 .LBB0_996
.LBB0_1011:
	s_ashr_i32 s9, s8, 31
	s_lshl_b64 s[16:17], s[8:9], 1
	v_lshl_add_u64 v[24:25], v[108:109], 0, s[16:17]
	v_lshl_add_u64 v[26:27], v[114:115], 0, s[16:17]
	v_lshl_add_u64 v[56:57], v[116:117], 0, s[16:17]
	global_load_dwordx4 v[72:75], v[24:25], off offset:128
	s_nop 0
	global_load_dwordx4 v[24:27], v[26:27], off offset:128
	s_nop 0
	global_load_dwordx4 v[56:59], v[56:57], off offset:128
	s_cmp_gt_i32 s3, 3
	s_cselect_b64 s[16:17], -1, 0
	s_cmp_lt_i32 s3, 4
	s_cbranch_scc1 .LBB0_997
.LBB0_1012:
	s_ashr_i32 s9, s8, 31
	s_lshl_b64 s[18:19], s[8:9], 1
	v_lshl_add_u64 v[20:21], v[108:109], 0, s[18:19]
	v_lshl_add_u64 v[22:23], v[114:115], 0, s[18:19]
	v_lshl_add_u64 v[52:53], v[116:117], 0, s[18:19]
	global_load_dwordx4 v[76:79], v[20:21], off offset:192
	s_nop 0
	global_load_dwordx4 v[20:23], v[22:23], off offset:192
	s_nop 0
	global_load_dwordx4 v[52:55], v[52:53], off offset:192
	s_cmp_gt_i32 s3, 4
	s_cselect_b64 s[18:19], -1, 0
	s_cmp_lt_i32 s3, 5
	s_cbranch_scc1 .LBB0_998
.LBB0_1013:
	s_ashr_i32 s9, s8, 31
	s_lshl_b64 s[20:21], s[8:9], 1
	v_lshl_add_u64 v[16:17], v[108:109], 0, s[20:21]
	v_lshl_add_u64 v[18:19], v[114:115], 0, s[20:21]
	v_lshl_add_u64 v[48:49], v[116:117], 0, s[20:21]
	global_load_dwordx4 v[80:83], v[16:17], off offset:256
	s_nop 0
	global_load_dwordx4 v[16:19], v[18:19], off offset:256
	s_nop 0
	global_load_dwordx4 v[48:51], v[48:49], off offset:256
	s_cmp_gt_i32 s3, 5
	s_cselect_b64 s[20:21], -1, 0
	s_cmp_lt_i32 s3, 6
	s_cbranch_scc1 .LBB0_999
.LBB0_1014:
	s_ashr_i32 s9, s8, 31
	s_lshl_b64 s[22:23], s[8:9], 1
	v_lshl_add_u64 v[12:13], v[108:109], 0, s[22:23]
	v_lshl_add_u64 v[14:15], v[114:115], 0, s[22:23]
	v_lshl_add_u64 v[44:45], v[116:117], 0, s[22:23]
	global_load_dwordx4 v[84:87], v[12:13], off offset:320
	s_nop 0
	global_load_dwordx4 v[12:15], v[14:15], off offset:320
	s_nop 0
	global_load_dwordx4 v[44:47], v[44:45], off offset:320
	s_cmp_gt_i32 s3, 6
	s_cselect_b64 s[22:23], -1, 0
	s_cmp_lt_i32 s3, 7
	s_cbranch_scc1 .LBB0_1000
.LBB0_1015:
	s_ashr_i32 s9, s8, 31
	s_lshl_b64 s[24:25], s[8:9], 1
	v_lshl_add_u64 v[8:9], v[108:109], 0, s[24:25]
	v_lshl_add_u64 v[10:11], v[114:115], 0, s[24:25]
	v_lshl_add_u64 v[40:41], v[116:117], 0, s[24:25]
	global_load_dwordx4 v[88:91], v[8:9], off offset:384
	s_nop 0
	global_load_dwordx4 v[8:11], v[10:11], off offset:384
	s_nop 0
	global_load_dwordx4 v[40:43], v[40:41], off offset:384
	s_cmp_gt_i32 s3, 7
	s_cselect_b64 s[24:25], -1, 0
	s_cmp_lt_i32 s3, 8
	s_cbranch_scc1 .LBB0_1001
.LBB0_1016:
	s_ashr_i32 s9, s8, 31
	s_lshl_b64 s[34:35], s[8:9], 1
	v_lshl_add_u64 v[4:5], v[108:109], 0, s[34:35]
	v_lshl_add_u64 v[6:7], v[114:115], 0, s[34:35]
	v_lshl_add_u64 v[36:37], v[116:117], 0, s[34:35]
	global_load_dwordx4 v[92:95], v[4:5], off offset:448
	s_nop 0
	global_load_dwordx4 v[4:7], v[6:7], off offset:448
	s_nop 0
	global_load_dwordx4 v[36:39], v[36:37], off offset:448
	s_andn2_b64 vcc, exec, s[10:11]
	s_cbranch_vccz .LBB0_1002
	s_branch .LBB0_1003

; template <class SE> __device__ __forceinline__ void skinny_gemm(const Frame& F, const bf16* Am, const bf16* Bt, int ntiles, int K, const SE& E) {
;     ...
;         for (int s0 = sb; s0 < se; s0 += 8) {
;             const int n = (se - s0) < 8 ? (se - s0) : 8;
;             bf16x8 av[8], bv[8], cv[8];
; #pragma unroll
;             for (int q = 0; q < 8; ++q) if (q < n) { av[q] = *(const bf16x8*)(ap + 32 * (s0 + q)); bv[q] = *(const bf16x8*)(b0 + 32 * (s0 + q)); if (SE::DUAL) cv[q] = *(const bf16x8*)(b1 + 32 * (s0 + q)); }
.LBB0_1113:
	s_cmp_gt_i32 s7, 0
	s_cselect_b64 s[10:11], -1, 0
	s_cmp_lt_i32 s7, 1
	s_cbranch_scc1 .LBB0_1115
	s_ashr_i32 s9, s8, 31
	s_lshl_b64 s[12:13], s[8:9], 1
	v_lshl_add_u64 v[32:33], v[74:75], 0, s[12:13]
	v_lshl_add_u64 v[0:1], v[68:69], 0, s[12:13]
	global_load_dwordx4 v[0:3], v[0:1], off
	s_nop 0
	global_load_dwordx4 v[32:35], v[32:33], off

; template <class SE> __device__ __forceinline__ void skinny_gemm(const Frame& F, const bf16* Am, const bf16* Bt, int ntiles, int K, const SE& E) {
;     ...
;         for (int s0 = sb; s0 < se; s0 += 8) {
;             const int n = (se - s0) < 8 ? (se - s0) : 8;
;             bf16x8 av[8], bv[8], cv[8];
; #pragma unroll
;             for (int q = 0; q < 8; ++q) if (q < n) { av[q] = *(const bf16x8*)(ap + 32 * (s0 + q)); bv[q] = *(const bf16x8*)(b0 + 32 * (s0 + q)); if (SE::DUAL) cv[q] = *(const bf16x8*)(b1 + 32 * (s0 + q)); }
.LBB0_1131:
	s_ashr_i32 s9, s8, 31
	s_lshl_b64 s[14:15], s[8:9], 1
	v_lshl_add_u64 v[28:29], v[74:75], 0, s[14:15]
	v_lshl_add_u64 v[30:31], v[68:69], 0, s[14:15]
	global_load_dwordx4 v[36:39], v[30:31], off offset:64
	s_nop 0
	global_load_dwordx4 v[28:31], v[28:29], off offset:64
	s_cmp_gt_i32 s7, 2
	s_cselect_b64 s[14:15], -1, 0
	s_cmp_lt_i32 s7, 3
	s_cbranch_scc1 .LBB0_1117
.LBB0_1132:
	s_ashr_i32 s9, s8, 31
	s_lshl_b64 s[16:17], s[8:9], 1
	v_lshl_add_u64 v[24:25], v[74:75], 0, s[16:17]
	v_lshl_add_u64 v[26:27], v[68:69], 0, s[16:17]
	global_load_dwordx4 v[40:43], v[26:27], off offset:128
	s_nop 0
	global_load_dwordx4 v[24:27], v[24:25], off offset:128
	s_cmp_gt_i32 s7, 3
	s_cselect_b64 s[16:17], -1, 0
	s_cmp_lt_i32 s7, 4
	s_cbranch_scc1 .LBB0_1118
.LBB0_1133:
	s_ashr_i32 s9, s8, 31
	s_lshl_b64 s[18:19], s[8:9], 1
	v_lshl_add_u64 v[20:21], v[74:75], 0, s[18:19]
	v_lshl_add_u64 v[22:23], v[68:69], 0, s[18:19]
	global_load_dwordx4 v[44:47], v[22:23], off offset:192
	s_nop 0
	global_load_dwordx4 v[20:23], v[20:21], off offset:192
	s_cmp_gt_i32 s7, 4
	s_cselect_b64 s[18:19], -1, 0
	s_cmp_lt_i32 s7, 5
	s_cbranch_scc1 .LBB0_1119
.LBB0_1134:
	s_ashr_i32 s9, s8, 31
	s_lshl_b64 s[20:21], s[8:9], 1
	v_lshl_add_u64 v[16:17], v[74:75], 0, s[20:21]
	v_lshl_add_u64 v[18:19], v[68:69], 0, s[20:21]
	global_load_dwordx4 v[48:51], v[18:19], off offset:256
	s_nop 0
	global_load_dwordx4 v[16:19], v[16:17], off offset:256
	s_cmp_gt_i32 s7, 5
	s_cselect_b64 s[20:21], -1, 0
	s_cmp_lt_i32 s7, 6
	s_cbranch_scc1 .LBB0_1120
.LBB0_1135:
	s_ashr_i32 s9, s8, 31
	s_lshl_b64 s[22:23], s[8:9], 1
	v_lshl_add_u64 v[12:13], v[74:75], 0, s[22:23]
	v_lshl_add_u64 v[14:15], v[68:69], 0, s[22:23]
	global_load_dwordx4 v[52:55], v[14:15], off offset:320
	s_nop 0
	global_load_dwordx4 v[12:15], v[12:13], off offset:320
	s_cmp_gt_i32 s7, 6
	s_cselect_b64 s[22:23], -1, 0
	s_cmp_lt_i32 s7, 7
	s_cbranch_scc1 .LBB0_1121
.LBB0_1136:
	s_ashr_i32 s9, s8, 31
	s_lshl_b64 s[24:25], s[8:9], 1
	v_lshl_add_u64 v[8:9], v[74:75], 0, s[24:25]
	v_lshl_add_u64 v[10:11], v[68:69], 0, s[24:25]
	global_load_dwordx4 v[56:59], v[10:11], off offset:384
	s_nop 0
	global_load_dwordx4 v[8:11], v[8:9], off offset:384
	s_cmp_gt_i32 s7, 7
	s_cselect_b64 s[24:25], -1, 0
	s_cmp_lt_i32 s7, 8
	s_cbranch_scc1 .LBB0_1122
.LBB0_1137:
	s_ashr_i32 s9, s8, 31
	s_lshl_b64 s[34:35], s[8:9], 1
	v_lshl_add_u64 v[4:5], v[74:75], 0, s[34:35]
	v_lshl_add_u64 v[6:7], v[68:69], 0, s[34:35]
	global_load_dwordx4 v[60:63], v[6:7], off offset:448
	s_nop 0
	global_load_dwordx4 v[4:7], v[4:5], off offset:448
	s_andn2_b64 vcc, exec, s[10:11]
	s_cbranch_vccz .LBB0_1123
	s_branch .LBB0_1124
